# HGRN2 pass1/pass3: denormal-input guard and inf-select of logf removed (f >= 1e-20, bit-identical); 6 fewer VALU per element
# speedup vs baseline: 1.0128x; 1.0128x over previous
; __device__ __forceinline__ float sigm_(float x) { return __builtin_amdgcn_rcpf(1.0f + __expf(-x)); }
; __device__ __forceinline__ float gelu_(float x) { return x * sigm_(1.5957691216f * (x + 0.044715f * x * x * x)); }
.LBB0_98:
	v_mul_f32_e32 v119, 0xbfb8aa3b, v227
	v_exp_f32_e32 v119, v119
	s_mov_b32 s14, 0x800000
	v_mul_f32_e32 v226, 0xbfb8aa3b, v226
	v_exp_f32_e32 v226, v226
	v_add_f32_e32 v119, 1.0, v119
	v_rcp_f32_e32 v119, v119
	s_mov_b32 s15, 0x3f317217
	v_add_f32_e32 v226, 1.0, v226
	v_rcp_f32_e32 v226, v226
	s_mov_b32 s16, 0x7f800000
	v_mul_f32_e32 v230, 0xbfb8aa3b, v230
	v_exp_f32_e32 v230, v230
	v_mul_f32_e32 v232, 0xbfb8aa3b, v232
	v_exp_f32_e32 v232, v232
	v_mul_f32_e32 v234, 0xbfb8aa3b, v234
	v_add_f32_e32 v230, 1.0, v230
	v_rcp_f32_e32 v230, v230
	v_add_f32_e32 v232, 1.0, v232
	v_rcp_f32_e32 v232, v232
	v_exp_f32_e32 v234, v234
	v_mul_f32_e32 v236, 0xbfb8aa3b, v236
	v_exp_f32_e32 v236, v236
	v_mul_f32_e32 v225, 0xbfb8aa3b, v225
	v_add_f32_e32 v234, 1.0, v234
	v_rcp_f32_e32 v234, v234
	v_add_f32_e32 v236, 1.0, v236
	v_rcp_f32_e32 v236, v236
	v_exp_f32_e32 v225, v225
	v_mul_f32_e32 v224, 0xbfb8aa3b, v224
	v_exp_f32_e32 v224, v224
	v_mul_f32_e32 v223, 0xbfb8aa3b, v223
	v_add_f32_e32 v225, 1.0, v225
	v_rcp_f32_e32 v225, v225
	v_add_f32_e32 v224, 1.0, v224
	v_rcp_f32_e32 v224, v224
	v_exp_f32_e32 v223, v223
	v_mul_f32_e32 v222, 0xbfb8aa3b, v222
	v_exp_f32_e32 v222, v222
	v_mul_f32_e32 v135, 0xbfb8aa3b, v135
	v_add_f32_e32 v223, 1.0, v223
	v_rcp_f32_e32 v223, v223
	v_add_f32_e32 v222, 1.0, v222
	v_rcp_f32_e32 v222, v222
	v_exp_f32_e32 v135, v135
	v_mul_f32_e32 v134, 0xbfb8aa3b, v134
	v_exp_f32_e32 v134, v134
	v_mul_f32_e32 v133, 0xbfb8aa3b, v133
	v_add_f32_e32 v135, 1.0, v135
	v_rcp_f32_e32 v135, v135
	v_add_f32_e32 v134, 1.0, v134
	v_rcp_f32_e32 v134, v134
	v_exp_f32_e32 v133, v133
	v_mul_f32_e32 v132, 0xbfb8aa3b, v132
	v_exp_f32_e32 v132, v132
	v_mul_f32_e32 v131, 0xbfb8aa3b, v131
	v_add_f32_e32 v133, 1.0, v133
	v_rcp_f32_e32 v133, v133
	v_add_f32_e32 v132, 1.0, v132
	v_rcp_f32_e32 v132, v132
	v_exp_f32_e32 v131, v131
	v_mul_f32_e32 v130, 0xbfb8aa3b, v130
	v_exp_f32_e32 v130, v130
	v_add_f32_e32 v131, 1.0, v131
	v_rcp_f32_e32 v131, v131
	v_add_f32_e32 v130, 1.0, v130
	v_rcp_f32_e32 v130, v130
	s_waitcnt vmcnt(58)
	v_sub_f32_e32 v229, 1.0, v228
	v_fma_f32 v119, v119, v229, v228
	v_max_f32_e32 v119, 0x1e3ce508, v119
	v_fma_f32 v226, v226, v229, v228
	v_max_f32_e32 v226, 0x1e3ce508, v226
	v_log_f32_e32 v227, v119
	v_fma_f32 v230, v230, v229, v228
	v_max_f32_e32 v230, 0x1e3ce508, v230
	v_fma_f32 v232, v232, v229, v228
	v_mul_f32_e32 v231, 0x3f317217, v227
	v_fma_f32 v231, v227, s15, -v231
	v_fmac_f32_e32 v231, 0x3377d1cf, v227
	v_fmac_f32_e32 v231, 0x3f317217, v227
	v_max_f32_e32 v232, 0x1e3ce508, v232
	v_fma_f32 v234, v234, v229, v228
	v_mov_b32_e32 v227, v231
	v_max_f32_e32 v234, 0x1e3ce508, v234
	v_log_f32_e32 v231, v226
	v_fma_f32 v236, v236, v229, v228
	v_max_f32_e32 v236, 0x1e3ce508, v236
	v_fma_f32 v225, v225, v229, v228
	v_mul_f32_e32 v233, 0x3f317217, v231
	v_fma_f32 v233, v231, s15, -v233
	v_fmac_f32_e32 v233, 0x3377d1cf, v231
	v_fmac_f32_e32 v233, 0x3f317217, v231
	v_max_f32_e32 v225, 0x1e3ce508, v225
	v_fma_f32 v224, v224, v229, v228
	v_mov_b32_e32 v231, v233
	v_max_f32_e32 v224, 0x1e3ce508, v224
	v_log_f32_e32 v233, v230
	v_fma_f32 v223, v223, v229, v228
	v_max_f32_e32 v223, 0x1e3ce508, v223
	v_fma_f32 v222, v222, v229, v228
	v_mul_f32_e32 v235, 0x3f317217, v233
	v_fma_f32 v235, v233, s15, -v235
	v_fmac_f32_e32 v235, 0x3377d1cf, v233
	v_fmac_f32_e32 v235, 0x3f317217, v233
	v_max_f32_e32 v222, 0x1e3ce508, v222
	v_fma_f32 v135, v135, v229, v228
	v_mov_b32_e32 v233, v235
	v_fma_f32 v134, v134, v229, v228
	v_log_f32_e32 v235, v232
	v_fma_f32 v133, v133, v229, v228
	v_max_f32_e32 v133, 0x1e3ce508, v133
	v_fma_f32 v132, v132, v229, v228
	v_mul_f32_e32 v237, 0x3f317217, v235
	v_fma_f32 v237, v235, s15, -v237
	v_fmac_f32_e32 v237, 0x3377d1cf, v235
	v_fmac_f32_e32 v237, 0x3f317217, v235
	v_fma_f32 v131, v131, v229, v228
	v_max_f32_e32 v131, 0x1e3ce508, v131
	v_mov_b32_e32 v235, v237
	v_fmac_f32_e32 v228, v130, v229
	v_log_f32_e32 v237, v234
	v_max_f32_e32 v228, 0x1e3ce508, v228
	v_mul_f32_e32 v238, 0x3f317217, v237
	v_fma_f32 v238, v237, s15, -v238
	v_fmac_f32_e32 v238, 0x3377d1cf, v237
	v_fmac_f32_e32 v238, 0x3f317217, v237
	s_nop 1
	v_mov_b32_e32 v237, v238
	s_nop 0
	v_log_f32_e32 v238, v236
	s_nop 0
	v_mul_f32_e32 v239, 0x3f317217, v238
	v_fma_f32 v239, v238, s15, -v239
	v_fmac_f32_e32 v239, 0x3377d1cf, v238
	v_fmac_f32_e32 v239, 0x3f317217, v238
	s_nop 1
	v_mov_b32_e32 v238, v239
	s_nop 0
	v_log_f32_e32 v239, v225
	s_nop 0
	v_mul_f32_e32 v240, 0x3f317217, v239
	v_fma_f32 v240, v239, s15, -v240
	v_fmac_f32_e32 v240, 0x3377d1cf, v239
	v_fmac_f32_e32 v240, 0x3f317217, v239
	s_nop 1
	v_mov_b32_e32 v239, v240
	s_nop 0
	v_log_f32_e32 v240, v224
	s_nop 0
	v_mul_f32_e32 v241, 0x3f317217, v240
	v_fma_f32 v241, v240, s15, -v241
	v_fmac_f32_e32 v241, 0x3377d1cf, v240
	v_fmac_f32_e32 v241, 0x3f317217, v240
	s_nop 1
	v_mov_b32_e32 v240, v241
	s_nop 0
	v_log_f32_e32 v241, v223
	s_nop 0
	v_mul_f32_e32 v242, 0x3f317217, v241
	v_fma_f32 v242, v241, s15, -v242
	v_fmac_f32_e32 v242, 0x3377d1cf, v241
	v_fmac_f32_e32 v242, 0x3f317217, v241
	s_nop 1
	v_mov_b32_e32 v241, v242
	s_nop 0
	v_log_f32_e32 v242, v222
	s_nop 0
	v_mul_f32_e32 v243, 0x3f317217, v242
	v_fma_f32 v243, v242, s15, -v243
	v_fmac_f32_e32 v243, 0x3377d1cf, v242
	v_fmac_f32_e32 v243, 0x3f317217, v242
	s_nop 1
	v_mov_b32_e32 v242, v243
	v_mov_b32_e32 v248, v242
	v_max_f32_e32 v242, 0x1e3ce508, v135
	s_nop 1
	v_log_f32_e32 v135, v242
	s_nop 0
	v_mul_f32_e32 v243, 0x3f317217, v135
	v_fma_f32 v243, v135, s15, -v243
	v_fmac_f32_e32 v243, 0x3377d1cf, v135
	v_fmac_f32_e32 v243, 0x3f317217, v135
	s_nop 1
	v_mov_b32_e32 v135, v243
	v_max_f32_e32 v243, 0x1e3ce508, v134
	s_nop 1
	v_log_f32_e32 v134, v243
	s_nop 0
	v_mul_f32_e32 v244, 0x3f317217, v134
	v_fma_f32 v244, v134, s15, -v244
	v_fmac_f32_e32 v244, 0x3377d1cf, v134
	v_fmac_f32_e32 v244, 0x3f317217, v134
	s_nop 1
	v_mov_b32_e32 v134, v244
	s_nop 0
	v_log_f32_e32 v244, v133
	s_nop 0
	v_mul_f32_e32 v245, 0x3f317217, v244
	v_fma_f32 v245, v244, s15, -v245
	v_fmac_f32_e32 v245, 0x3377d1cf, v244
	v_fmac_f32_e32 v245, 0x3f317217, v244
	s_nop 1
	v_mov_b32_e32 v244, v245
	v_mov_b32_e32 v250, v244
	v_max_f32_e32 v244, 0x1e3ce508, v132
	s_nop 1
	v_log_f32_e32 v132, v244
	s_nop 0
	v_mul_f32_e32 v245, 0x3f317217, v132
	v_fma_f32 v245, v132, s15, -v245
	v_fmac_f32_e32 v245, 0x3377d1cf, v132
	v_fmac_f32_e32 v245, 0x3f317217, v132
	s_nop 1
	v_mov_b32_e32 v132, v245
	s_nop 0
	v_log_f32_e32 v245, v131
	s_nop 0
	v_mul_f32_e32 v246, 0x3f317217, v245
	v_fma_f32 v246, v245, s15, -v246
	v_fmac_f32_e32 v246, 0x3377d1cf, v245
	v_fmac_f32_e32 v246, 0x3f317217, v245
	s_nop 1
	v_mov_b32_e32 v245, v246
	v_mov_b32_e32 v251, v245
	s_nop 0
	v_log_f32_e32 v130, v228
	s_nop 0
	v_mul_f32_e32 v229, 0x3f317217, v130
	v_fma_f32 v229, v130, s15, -v229
	v_fmac_f32_e32 v229, 0x3377d1cf, v130
	v_fmac_f32_e32 v229, 0x3f317217, v130
	s_nop 1
	v_mov_b32_e32 v130, v229
	v_mov_b32_e32 v229, v130
	v_add_f32_e32 v130, 0, v227
	v_add_f32_e32 v245, v231, v130
	v_add_f32_e32 v246, v233, v245
	v_add_f32_e32 v247, v235, v246
	v_add_f32_e32 v237, v237, v247
	v_add_f32_e32 v238, v238, v237
	v_add_f32_e32 v239, v239, v238
	v_add_f32_e32 v240, v240, v239
	v_add_f32_e32 v241, v241, v240
	v_add_f32_e32 v248, v248, v241
	v_add_f32_e32 v249, v135, v248
	v_add_f32_e32 v231, v134, v249
	v_add_f32_e32 v233, v250, v231
	v_add_f32_e32 v235, v132, v233
	v_add_f32_e32 v227, v251, v235
	v_add_f32_e32 v229, v229, v227
	ds_write_b32 v113, v229
	s_waitcnt lgkmcnt(0)
	s_barrier
	ds_read2st64_b32 v[134:135], v136 offset1:2
	v_mov_b32_e32 v132, 0
	s_and_saveexec_b64 s[40:41], s[6:7]
	s_cbranch_execz .LBB0_106
	ds_read_b32 v250, v136 offset:1024
	v_cmp_lt_i32_e32 vcc, 1, v3
	s_mov_b64 s[14:15], 0
	s_and_saveexec_b64 s[16:17], vcc
	s_xor_b64 s[54:55], exec, s[16:17]
	s_cbranch_execz .LBB0_108
	v_cmp_eq_u32_e32 vcc, 2, v3
	s_mov_b64 s[14:15], -1
	s_and_saveexec_b64 s[62:63], vcc
	s_cbranch_execz .LBB0_102
	s_waitcnt lgkmcnt(1)
	v_add_f32_e32 v132, v134, v135
	s_xor_b64 s[14:15], exec, -1

; __device__ __forceinline__ float sigm_(float x) { return __builtin_amdgcn_rcpf(1.0f + __expf(-x)); }
; __device__ __forceinline__ float gelu_(float x) { return x * sigm_(1.5957691216f * (x + 0.044715f * x * x * x)); }
.LBB0_130:
	s_and_b32 s10, s14, 0x180
	v_mul_f32_e32 v37, 0xbfb8aa3b, v38
	v_exp_f32_e32 v37, v37
	s_mov_b32 s14, 0x800000
	v_mul_f32_e32 v39, 0xbfb8aa3b, v39
	v_exp_f32_e32 v39, v39
	v_add_f32_e32 v37, 1.0, v37
	v_rcp_f32_e32 v37, v37
	s_mov_b32 s15, 0x3f317217
	v_add_f32_e32 v39, 1.0, v39
	v_rcp_f32_e32 v39, v39
	s_mov_b32 s16, 0x7f800000
	v_mul_f32_e32 v40, 0xbfb8aa3b, v40
	v_exp_f32_e32 v40, v40
	v_mul_f32_e32 v41, 0xbfb8aa3b, v41
	v_exp_f32_e32 v41, v41
	v_mul_f32_e32 v42, 0xbfb8aa3b, v42
	v_add_f32_e32 v40, 1.0, v40
	v_rcp_f32_e32 v40, v40
	v_add_f32_e32 v41, 1.0, v41
	v_rcp_f32_e32 v41, v41
	v_exp_f32_e32 v42, v42
	v_mul_f32_e32 v43, 0xbfb8aa3b, v43
	v_exp_f32_e32 v43, v43
	v_mul_f32_e32 v44, 0xbfb8aa3b, v44
	v_add_f32_e32 v42, 1.0, v42
	v_rcp_f32_e32 v42, v42
	v_add_f32_e32 v43, 1.0, v43
	v_rcp_f32_e32 v43, v43
	v_exp_f32_e32 v44, v44
	v_mul_f32_e32 v45, 0xbfb8aa3b, v45
	v_exp_f32_e32 v45, v45
	v_mul_f32_e32 v46, 0xbfb8aa3b, v46
	v_add_f32_e32 v44, 1.0, v44
	v_rcp_f32_e32 v44, v44
	v_add_f32_e32 v45, 1.0, v45
	v_rcp_f32_e32 v45, v45
	v_exp_f32_e32 v46, v46
	v_mul_f32_e32 v47, 0xbfb8aa3b, v47
	v_exp_f32_e32 v47, v47
	v_mul_f32_e32 v48, 0xbfb8aa3b, v48
	v_add_f32_e32 v46, 1.0, v46
	v_rcp_f32_e32 v46, v46
	v_add_f32_e32 v47, 1.0, v47
	v_rcp_f32_e32 v47, v47
	v_exp_f32_e32 v48, v48
	v_mul_f32_e32 v49, 0xbfb8aa3b, v49
	v_exp_f32_e32 v49, v49
	v_mul_f32_e32 v50, 0xbfb8aa3b, v50
	v_add_f32_e32 v48, 1.0, v48
	v_rcp_f32_e32 v48, v48
	v_add_f32_e32 v49, 1.0, v49
	v_rcp_f32_e32 v49, v49
	v_exp_f32_e32 v50, v50
	v_mul_f32_e32 v51, 0xbfb8aa3b, v51
	v_exp_f32_e32 v51, v51
	v_mul_f32_e32 v52, 0xbfb8aa3b, v52
	v_add_f32_e32 v50, 1.0, v50
	v_rcp_f32_e32 v50, v50
	v_add_f32_e32 v51, 1.0, v51
	v_rcp_f32_e32 v51, v51
	v_exp_f32_e32 v52, v52
	v_mul_f32_e32 v53, 0xbfb8aa3b, v53
	v_exp_f32_e32 v53, v53
	v_add_f32_e32 v52, 1.0, v52
	v_rcp_f32_e32 v52, v52
	v_add_f32_e32 v53, 1.0, v53
	v_rcp_f32_e32 v53, v53
	s_waitcnt vmcnt(18)
	v_sub_f32_e32 v55, 1.0, v54
	v_fma_f32 v37, v37, v55, v54
	v_max_f32_e32 v38, 0x1e3ce508, v37
	v_fma_f32 v39, v39, v55, v54
	v_max_f32_e32 v39, 0x1e3ce508, v39
	v_log_f32_e32 v37, v38
	v_fma_f32 v40, v40, v55, v54
	v_max_f32_e32 v40, 0x1e3ce508, v40
	v_fma_f32 v41, v41, v55, v54
	v_mul_f32_e32 v56, 0x3f317217, v37
	v_fma_f32 v56, v37, s15, -v56
	v_fmac_f32_e32 v56, 0x3377d1cf, v37
	v_fmac_f32_e32 v56, 0x3f317217, v37
	v_max_f32_e32 v41, 0x1e3ce508, v41
	v_fma_f32 v42, v42, v55, v54
	v_mov_b32_e32 v37, v56
	v_max_f32_e32 v42, 0x1e3ce508, v42
	v_log_f32_e32 v56, v39
	v_fma_f32 v43, v43, v55, v54
	v_max_f32_e32 v43, 0x1e3ce508, v43
	v_fma_f32 v44, v44, v55, v54
	v_mul_f32_e32 v57, 0x3f317217, v56
	v_fma_f32 v57, v56, s15, -v57
	v_fmac_f32_e32 v57, 0x3377d1cf, v56
	v_fmac_f32_e32 v57, 0x3f317217, v56
	v_max_f32_e32 v44, 0x1e3ce508, v44
	v_fma_f32 v45, v45, v55, v54
	v_mov_b32_e32 v56, v57
	v_max_f32_e32 v45, 0x1e3ce508, v45
	v_log_f32_e32 v57, v40
	v_fma_f32 v46, v46, v55, v54
	v_max_f32_e32 v46, 0x1e3ce508, v46
	v_fma_f32 v47, v47, v55, v54
	v_mul_f32_e32 v58, 0x3f317217, v57
	v_fma_f32 v58, v57, s15, -v58
	v_fmac_f32_e32 v58, 0x3377d1cf, v57
	v_fmac_f32_e32 v58, 0x3f317217, v57
	v_max_f32_e32 v47, 0x1e3ce508, v47
	v_fma_f32 v48, v48, v55, v54
	v_mov_b32_e32 v57, v58
	v_max_f32_e32 v48, 0x1e3ce508, v48
	v_log_f32_e32 v58, v41
	v_fma_f32 v49, v49, v55, v54
	v_max_f32_e32 v49, 0x1e3ce508, v49
	v_fma_f32 v50, v50, v55, v54
	v_mul_f32_e32 v59, 0x3f317217, v58
	v_fma_f32 v59, v58, s15, -v59
	v_fmac_f32_e32 v59, 0x3377d1cf, v58
	v_fmac_f32_e32 v59, 0x3f317217, v58
	v_max_f32_e32 v50, 0x1e3ce508, v50
	v_fma_f32 v51, v51, v55, v54
	v_mov_b32_e32 v58, v59
	v_max_f32_e32 v51, 0x1e3ce508, v51
	v_log_f32_e32 v59, v42
	v_fma_f32 v52, v52, v55, v54
	v_max_f32_e32 v52, 0x1e3ce508, v52
	v_fmac_f32_e32 v54, v53, v55
	v_mul_f32_e32 v60, 0x3f317217, v59
	v_fma_f32 v60, v59, s15, -v60
	v_fmac_f32_e32 v60, 0x3377d1cf, v59
	v_fmac_f32_e32 v60, 0x3f317217, v59
	v_max_f32_e32 v53, 0x1e3ce508, v54
	s_nop 0
	v_mov_b32_e32 v59, v60
	s_nop 0
	v_log_f32_e32 v60, v43
	s_nop 0
	v_mul_f32_e32 v61, 0x3f317217, v60
	v_fma_f32 v61, v60, s15, -v61
	v_fmac_f32_e32 v61, 0x3377d1cf, v60
	v_fmac_f32_e32 v61, 0x3f317217, v60
	s_nop 1
	v_mov_b32_e32 v60, v61
	s_nop 0
	v_log_f32_e32 v61, v44
	s_nop 0
	v_mul_f32_e32 v86, 0x3f317217, v61
	v_fma_f32 v86, v61, s15, -v86
	v_fmac_f32_e32 v86, 0x3377d1cf, v61
	v_fmac_f32_e32 v86, 0x3f317217, v61
	s_nop 1
	v_mov_b32_e32 v61, v86
	s_nop 0
	v_log_f32_e32 v86, v45
	s_nop 0
	v_mul_f32_e32 v87, 0x3f317217, v86
	v_fma_f32 v87, v86, s15, -v87
	v_fmac_f32_e32 v87, 0x3377d1cf, v86
	v_fmac_f32_e32 v87, 0x3f317217, v86
	s_nop 1
	v_mov_b32_e32 v86, v87
	s_nop 0
	v_log_f32_e32 v87, v46
	s_nop 0
	v_mul_f32_e32 v88, 0x3f317217, v87
	v_fma_f32 v88, v87, s15, -v88
	v_fmac_f32_e32 v88, 0x3377d1cf, v87
	v_fmac_f32_e32 v88, 0x3f317217, v87
	s_nop 1
	v_mov_b32_e32 v87, v88
	s_nop 0
	v_log_f32_e32 v88, v47
	s_nop 0
	v_mul_f32_e32 v89, 0x3f317217, v88
	v_fma_f32 v89, v88, s15, -v89
	v_fmac_f32_e32 v89, 0x3377d1cf, v88
	v_fmac_f32_e32 v89, 0x3f317217, v88
	s_nop 1
	v_mov_b32_e32 v88, v89
	v_mov_b32_e32 v94, v88
	s_nop 0
	v_log_f32_e32 v88, v48
	s_nop 0
	v_mul_f32_e32 v89, 0x3f317217, v88
	v_fma_f32 v89, v88, s15, -v89
	v_fmac_f32_e32 v89, 0x3377d1cf, v88
	v_fmac_f32_e32 v89, 0x3f317217, v88
	s_nop 1
	v_mov_b32_e32 v88, v89
	v_mov_b32_e32 v95, v88
	s_nop 0
	v_log_f32_e32 v88, v49
	s_nop 0
	v_mul_f32_e32 v89, 0x3f317217, v88
	v_fma_f32 v89, v88, s15, -v89
	v_fmac_f32_e32 v89, 0x3377d1cf, v88
	v_fmac_f32_e32 v89, 0x3f317217, v88
	s_nop 1
	v_mov_b32_e32 v88, v89
	v_mov_b32_e32 v96, v88
	s_nop 0
	v_log_f32_e32 v88, v50
	s_nop 0
	v_mul_f32_e32 v89, 0x3f317217, v88
	v_fma_f32 v89, v88, s15, -v89
	v_fmac_f32_e32 v89, 0x3377d1cf, v88
	v_fmac_f32_e32 v89, 0x3f317217, v88
	s_nop 1
	v_mov_b32_e32 v88, v89
	v_mov_b32_e32 v97, v88
	s_nop 0
	v_log_f32_e32 v88, v51
	s_nop 0
	v_mul_f32_e32 v89, 0x3f317217, v88
	v_fma_f32 v89, v88, s15, -v89
	v_fmac_f32_e32 v89, 0x3377d1cf, v88
	v_fmac_f32_e32 v89, 0x3f317217, v88
	s_nop 1
	v_mov_b32_e32 v88, v89
	v_mov_b32_e32 v98, v88
	s_nop 0
	v_log_f32_e32 v88, v52
	s_nop 0
	v_mul_f32_e32 v89, 0x3f317217, v88
	v_fma_f32 v89, v88, s15, -v89
	v_fmac_f32_e32 v89, 0x3377d1cf, v88
	v_fmac_f32_e32 v89, 0x3f317217, v88
	s_nop 1
	v_mov_b32_e32 v88, v89
	v_mov_b32_e32 v99, v88
	s_nop 0
	v_log_f32_e32 v54, v53
	s_nop 0
	v_mul_f32_e32 v55, 0x3f317217, v54
	v_fma_f32 v55, v54, s15, -v55
	v_fmac_f32_e32 v55, 0x3377d1cf, v54
	v_fmac_f32_e32 v55, 0x3f317217, v54
	s_nop 1
	v_mov_b32_e32 v54, v55
	v_mov_b32_e32 v55, v54
	v_add_f32_e32 v54, 0, v37
	v_add_f32_e32 v88, v56, v54
	v_add_f32_e32 v89, v57, v88
	v_add_f32_e32 v90, v58, v89
	v_add_f32_e32 v91, v59, v90
	v_add_f32_e32 v92, v60, v91
	v_add_f32_e32 v93, v61, v92
	v_add_f32_e32 v86, v86, v93
	v_add_f32_e32 v87, v87, v86
	v_add_f32_e32 v94, v94, v87
	v_add_f32_e32 v95, v95, v94
	v_add_f32_e32 v96, v96, v95
	v_add_f32_e32 v97, v97, v96
	v_add_f32_e32 v98, v98, v97
	v_add_f32_e32 v37, v99, v98
	v_add_f32_e32 v55, v55, v37
	ds_write_b32 v25, v55 offset:36864
	s_waitcnt lgkmcnt(0)
	s_barrier
	ds_read2st64_b32 v[56:57], v64 offset0:144 offset1:146
	ds_read2st64_b32 v[60:61], v64 offset0:148 offset1:150
	v_mov_b32_e32 v59, 0
	s_and_saveexec_b64 s[10:11], s[8:9]
	s_cbranch_execz .LBB0_138
	v_cmp_lt_i32_e32 vcc, 1, v63
	s_mov_b64 s[14:15], 0
	s_and_saveexec_b64 s[16:17], vcc
	s_xor_b64 s[28:29], exec, s[16:17]
	s_cbranch_execz .LBB0_140
	v_cmp_eq_u32_e32 vcc, 2, v63
	s_mov_b64 s[14:15], -1
	s_and_saveexec_b64 s[30:31], vcc
	s_cbranch_execz .LBB0_134
	s_waitcnt lgkmcnt(1)
	v_add_f32_e32 v59, v56, v57
	s_xor_b64 s[14:15], exec, -1
